# split pooling: 3584 items in P2 tail, rest in P1
# speedup vs baseline: 1.0016x; 1.0016x over previous
; #define GAS __attribute__((address_space(1)))
; __device__ __forceinline__ void prep_phase(Frame& F, CArgs a, int l, unsigned long long& tm_acc) {
;     ...
;         GAS bf16_t* P = (GAS bf16_t*)(ws + WS_POOL);
;         const int gw = F.blk * 8 + F.wave, NGW = F.G * 8;
;         for (int wi = gw; wi < M; wi += NGW) {
;             const int g = wi & 3, row = (wi >> 2) * 4 + (F.lane >> 4), cg = g * 16 + (F.lane & 15);
;             int t, L; if (row < MC) { t = row & 255; L = CTXL; } else { t = (row - MC) & 2047; L = SEQ; }
.LBB0_611:
	s_cmp_le_i32 s96, s4
	s_cselect_b64 s[4:5], -1, 0
	s_and_b64 s[58:59], s[4:5], s[8:9]
	s_andn2_b64 vcc, exec, s[58:59]
	s_cbranch_vccnz .LBB0_677
	s_load_dwordx2 s[6:7], s[0:1], 0x130
	v_readfirstlane_b32 s8, v0
	s_ashr_i32 s4, s8, 6
	s_waitcnt lgkmcnt(0)
	s_add_u32 s22, s6, 0x2a600000
	v_readlane_b32 s5, v254, 54
	s_addc_u32 s23, s7, 0
	s_add_i32 s5, s4, s5
	s_addk_i32 s5, 0xe00
	s_cmpk_gt_i32 s5, 0x23ff
	v_and_b32_e32 v118, 63, v0
	s_cbranch_scc1 .LBB0_626
	s_waitcnt vmcnt(0)
	v_lshlrev_b32_e32 v2, 4, v118
	s_bfe_u32 s10, s8, 0x20006
	v_and_b32_e32 v2, 0xf0, v2
	v_lshl_or_b32 v202, s10, 8, v2
	v_lshl_add_u64 v[2:3], s[6:7], 0, v[202:203]
	s_mov_b64 s[8:9], 0x3c600000
	v_lshrrev_b32_e32 v1, 4, v118
	s_waitcnt vmcnt(16)
	v_lshl_add_u64 v[30:31], s[22:23], 0, v[202:203]
	v_lshl_add_u64 v[32:33], v[2:3], 0, s[8:9]
	s_branch .LBB0_615

; #define GAS __attribute__((address_space(1)))
; __device__ __forceinline__ unsigned pk2(float lo, float hi) { unsigned r; asm("v_cvt_pk_bf16_f32 %0, %1, %2" : "=v"(r) : "v"(lo), "v"(hi)); return r; }
; __device__ __forceinline__ void prep_phase(Frame& F, CArgs a, int l, unsigned long long& tm_acc) {
;     ...
;         const int gw = F.blk * 8 + F.wave, NGW = F.G * 8;
;         for (int wi = gw; wi < M; wi += NGW) {
;             const int g = wi & 3, row = (wi >> 2) * 4 + (F.lane >> 4), cg = g * 16 + (F.lane & 15);
;             int t, L; if (row < MC) { t = row & 255; L = CTXL; } else { t = (row - MC) & 2047; L = SEQ; }
;             const GAS bf16_t* zc = Z + (size_t)(row - t) * DIN + cg * 8;
;             float s[8] = {0.f, 0.f, 0.f, 0.f, 0.f, 0.f, 0.f, 0.f}; int cnt = 0;
;             auto body = [&](auto WC) { constexpr int W = decltype(WC)::value;
;                 u32x4 v[W]; float mk[W];
; #pragma unroll
;                 for (int j = 0; j < W; ++j) { const int tt = t - W / 2 + j; const bool ok = tt >= 0 && tt < L; mk[j] = ok ? 1.f : 0.f; cnt += ok ? 1 : 0; v[j] = *(const GAS u32x4*)(zc + (size_t)(ok ? tt : t) * DIN); }
; #pragma unroll
;                 for (int j = 0; j < W; ++j) { s[0] += mk[j] * bflo(v[j].x); s[1] += mk[j] * bfhi(v[j].x); s[2] += mk[j] * bflo(v[j].y); s[3] += mk[j] * bfhi(v[j].y);
;                     s[4] += mk[j] * bflo(v[j].z); s[5] += mk[j] * bfhi(v[j].z); s[6] += mk[j] * bflo(v[j].w); s[7] += mk[j] * bfhi(v[j].w); } };
;             if (g == 0) body(std::integral_constant<int, 2>{}); else if (g == 1) body(std::integral_constant<int, 4>{}); else if (g == 2) body(std::integral_constant<int, 8>{}); else body(std::integral_constant<int, 16>{});
;             const u32x4 sv = *(const GAS u32x4*)(zc + (size_t)t * DIN);
;             const float inv = 1.0f / (float)cnt;
;             u32x4 o; o.x = pk2(s[0] * inv - bflo(sv.x), s[1] * inv - bfhi(sv.x)); o.y = pk2(s[2] * inv - bflo(sv.y), s[3] * inv - bfhi(sv.y));
;             o.z = pk2(s[4] * inv - bflo(sv.z), s[5] * inv - bfhi(sv.z)); o.w = pk2(s[6] * inv - bflo(sv.w), s[7] * inv - bfhi(sv.w));
;             *(GAS u32x4*)(P + (size_t)row * 512 + cg * 8) = o;
.LBB0_920:
	s_cmpk_lt_i32 s2, 32
	s_cbranch_scc1 .Lpa_exit
	s_load_dwordx2 s[6:7], s[0:1], 0x130
	v_readfirstlane_b32 s8, v0
	s_ashr_i32 s4, s8, 6
	s_waitcnt lgkmcnt(0)
	s_add_u32 s22, s6, 0x2a600000
	v_readlane_b32 s5, v254, 54
	s_addc_u32 s23, s7, 0
	s_add_i32 s5, s4, s5
	s_addk_i32 s5, 0xff00
	s_cmpk_gt_i32 s5, 0xdff
	v_and_b32_e32 v118, 63, v0
	s_cbranch_scc1 .Lpa_exit
	s_waitcnt vmcnt(0)
	v_lshlrev_b32_e32 v2, 4, v118
	s_bfe_u32 s10, s8, 0x20006
	v_and_b32_e32 v2, 0xf0, v2
	v_lshl_or_b32 v202, s10, 8, v2
	v_lshl_add_u64 v[2:3], s[6:7], 0, v[202:203]
	s_mov_b64 s[8:9], 0x3c600000
	v_lshrrev_b32_e32 v1, 4, v118
	s_waitcnt vmcnt(16)
	v_lshl_add_u64 v[30:31], s[22:23], 0, v[202:203]
	v_lshl_add_u64 v[32:33], v[2:3], 0, s[8:9]
	s_branch .Lpa_615
.Lpa_614:
	v_lshlrev_b32_e32 v4, 16, v5
	v_fma_f32 v12, v38, v4, v40
	v_and_b32_e32 v4, 0xffff0000, v5
	v_fmac_f32_e32 v41, v38, v4
	v_lshl_add_u64 v[4:5], v[36:37], 0, v[202:203]
	global_load_dwordx4 v[8:11], v[4:5], off
	s_waitcnt vmcnt(14)
	v_cvt_f32_u32_e32 v4, v45
	v_ashrrev_i32_e32 v35, 31, v34
	s_addk_i32 s5, 0x700
	s_cmpk_gt_i32 s5, 0xdff
	v_div_scale_f32 v5, s[8:9], v4, v4, 1.0
	v_rcp_f32_e32 v13, v5
	s_nop 0
	v_fma_f32 v14, -v5, v13, 1.0
	v_fmac_f32_e32 v13, v14, v13
	v_div_scale_f32 v14, vcc, 1.0, v4, 1.0
	v_mul_f32_e32 v15, v14, v13
	v_fma_f32 v16, -v5, v15, v14
	v_fmac_f32_e32 v15, v16, v13
	v_fma_f32 v5, -v5, v15, v14
	v_div_fmas_f32 v5, v5, v13, v15
	v_div_fixup_f32 v13, v5, v4, 1.0
	s_waitcnt vmcnt(0)
	v_lshlrev_b32_e32 v4, 16, v8
	v_and_b32_e32 v5, 0xffff0000, v8
	v_fma_f32 v4, v42, v13, -v4
	v_fma_f32 v5, v43, v13, -v5
	v_cvt_pk_bf16_f32 v4, v4, v5
	v_lshlrev_b32_e32 v5, 16, v9
	v_fma_f32 v2, v13, v2, -v5
	v_and_b32_e32 v5, 0xffff0000, v9
	v_fma_f32 v3, v13, v3, -v5
	v_cvt_pk_bf16_f32 v5, v2, v3
	v_lshlrev_b32_e32 v2, 16, v10
	v_and_b32_e32 v3, 0xffff0000, v10
	v_fma_f32 v2, v13, v6, -v2
	v_fma_f32 v3, v13, v7, -v3
	v_cvt_pk_bf16_f32 v6, v2, v3
	v_lshlrev_b32_e32 v2, 16, v11
	v_and_b32_e32 v3, 0xffff0000, v11
	v_fma_f32 v2, v12, v13, -v2
	v_fma_f32 v3, v41, v13, -v3
	v_cvt_pk_bf16_f32 v7, v2, v3
	v_lshlrev_b64 v[2:3], 10, v[34:35]
	v_lshl_add_u64 v[2:3], v[32:33], 0, v[2:3]
	global_store_dwordx4 v[2:3], v[4:7], off
	s_cbranch_scc1 .Lpa_exit
